# weight-transpose loops (P0 + P3 tail): 4 row loads + 4 gain loads issued together with counted waits instead of one load per round trip
# speedup vs baseline: 1.0249x; 1.0249x over previous
.LBB0_22:
	v_mov_b32_e32 v100, 1.0
	v_mov_b32_e32 v101, 1.0
	v_mov_b32_e32 v102, 1.0
	v_mov_b32_e32 v103, 1.0
	s_andn2_b64 vcc, exec, s[22:23]
	s_cbranch_vccnz .Lp0a_nogain
	global_load_dword v100, v[30:31], off
	global_load_dword v101, v[26:27], off
	global_load_dword v102, v[22:23], off
	global_load_dword v103, v[18:19], off
.Lp0a_nogain:
	v_lshl_add_u64 v[84:85], v[16:17], 0, v[28:29]
	global_load_dwordx4 v[84:87], v[84:85], off
	v_lshl_add_u64 v[88:89], v[16:17], 0, v[24:25]
	global_load_dwordx4 v[88:91], v[88:89], off
	v_lshl_add_u64 v[92:93], v[16:17], 0, v[20:21]
	global_load_dwordx4 v[92:95], v[92:93], off
	v_lshl_add_u64 v[96:97], v[16:17], 0, v[2:3]
	global_load_dwordx4 v[96:99], v[96:97], off
	s_add_i32 s35, s34, -4
	v_xor_b32_e32 v64, s35, v33
	v_lshl_add_u32 v64, v64, 2, v56
	v_add_u32_e32 v64, s26, v64
	v_xor_b32_e32 v65, s34, v33
	v_lshl_add_u32 v65, v65, 2, v56
	v_add_u32_e32 v65, s26, v65
	s_mov_b64 s[38:39], 0x10000
	v_lshl_add_u64 v[16:17], v[16:17], 0, s[38:39]
	v_lshl_add_u64 v[18:19], v[18:19], 0, 64
	v_lshl_add_u64 v[22:23], v[22:23], 0, 64
	v_lshl_add_u64 v[26:27], v[26:27], 0, 64
	v_lshl_add_u64 v[30:31], v[30:31], 0, 64
	s_waitcnt vmcnt(3)
	v_pk_mul_f32 v[84:85], v[84:85], v[100:101] op_sel_hi:[1,0]
	v_pk_mul_f32 v[86:87], v[86:87], v[100:101] op_sel_hi:[1,0]
	ds_write_b128 v64, v[84:87] offset:16384
	s_waitcnt vmcnt(2)
	v_pk_mul_f32 v[88:89], v[88:89], v[100:101] op_sel:[0,1] op_sel_hi:[1,1]
	v_pk_mul_f32 v[90:91], v[90:91], v[100:101] op_sel:[0,1] op_sel_hi:[1,1]
	ds_write_b128 v64, v[88:91] offset:17408
	s_waitcnt vmcnt(1)
	v_pk_mul_f32 v[92:93], v[92:93], v[102:103] op_sel_hi:[1,0]
	v_pk_mul_f32 v[94:95], v[94:95], v[102:103] op_sel_hi:[1,0]
	ds_write_b128 v65, v[92:95] offset:18432
	s_waitcnt vmcnt(0)
	v_pk_mul_f32 v[96:97], v[96:97], v[102:103] op_sel:[0,1] op_sel_hi:[1,1]
	v_pk_mul_f32 v[98:99], v[98:99], v[102:103] op_sel:[0,1] op_sel_hi:[1,1]
	ds_write_b128 v65, v[96:99] offset:19456
	s_addk_i32 s26, 0x1000
	s_add_i32 s34, s34, 8
	s_cmp_lg_u32 s26, 0
	s_cbranch_scc1 .LBB0_22

.LBB0_39:
	v_mov_b32_e32 v100, 1.0
	v_mov_b32_e32 v101, 1.0
	v_mov_b32_e32 v102, 1.0
	v_mov_b32_e32 v103, 1.0
	s_andn2_b64 vcc, exec, s[24:25]
	s_cbranch_vccnz .Lp0b_nogain
	v_add_u32_e32 v24, -12, v18
	v_ashrrev_i32_e32 v25, 31, v24
	v_lshl_add_u64 v[26:27], v[24:25], 2, s[62:63]
	global_load_dword v100, v[26:27], off
	global_load_dword v101, v[20:21], off
	v_add_u32_e32 v24, -4, v18
	v_ashrrev_i32_e32 v25, 31, v24
	v_lshl_add_u64 v[26:27], v[24:25], 2, s[62:63]
	global_load_dword v102, v[26:27], off
	v_ashrrev_i32_e32 v19, 31, v18
	v_lshl_add_u64 v[26:27], v[18:19], 2, s[62:63]
	global_load_dword v103, v[26:27], off
.Lp0b_nogain:
	v_add_u32_e32 v24, -12, v18
	v_mad_i64_i32 v[84:85], s[38:39], v24, s12, v[16:17]
	global_load_dwordx4 v[84:87], v[84:85], off
	v_add_u32_e32 v24, -8, v18
	v_mad_i64_i32 v[88:89], s[38:39], v24, s12, v[16:17]
	global_load_dwordx4 v[88:91], v[88:89], off
	v_add_u32_e32 v24, -4, v18
	v_mad_i64_i32 v[92:93], s[38:39], v24, s12, v[16:17]
	global_load_dwordx4 v[92:95], v[92:93], off
	v_mad_i64_i32 v[96:97], s[38:39], v18, s12, v[16:17]
	global_load_dwordx4 v[96:99], v[96:97], off
	s_add_i32 s37, s36, -4
	v_xor_b32_e32 v19, s37, v33
	v_lshl_add_u32 v19, v19, 2, v56
	v_add_u32_e32 v19, s35, v19
	v_xor_b32_e32 v23, s36, v33
	v_lshl_add_u32 v23, v23, 2, v56
	v_add_u32_e32 v23, s35, v23
	s_waitcnt vmcnt(3)
	v_pk_mul_f32 v[84:85], v[84:85], v[100:101] op_sel_hi:[1,0]
	v_pk_mul_f32 v[86:87], v[86:87], v[100:101] op_sel_hi:[1,0]
	ds_write_b128 v19, v[84:87] offset:16384
	s_waitcnt vmcnt(2)
	v_pk_mul_f32 v[88:89], v[88:89], v[100:101] op_sel:[0,1] op_sel_hi:[1,1]
	v_pk_mul_f32 v[90:91], v[90:91], v[100:101] op_sel:[0,1] op_sel_hi:[1,1]
	ds_write_b128 v19, v[88:91] offset:17408
	s_waitcnt vmcnt(1)
	v_pk_mul_f32 v[92:93], v[92:93], v[102:103] op_sel_hi:[1,0]
	v_pk_mul_f32 v[94:95], v[94:95], v[102:103] op_sel_hi:[1,0]
	ds_write_b128 v23, v[92:95] offset:18432
	s_waitcnt vmcnt(0)
	v_pk_mul_f32 v[96:97], v[96:97], v[102:103] op_sel:[0,1] op_sel_hi:[1,1]
	v_pk_mul_f32 v[98:99], v[98:99], v[102:103] op_sel:[0,1] op_sel_hi:[1,1]
	ds_write_b128 v23, v[96:99] offset:19456
	s_addk_i32 s35, 0x1000
	s_add_i32 s36, s36, 8
	v_add_u32_e32 v18, 16, v18
	v_lshl_add_u64 v[20:21], v[20:21], 0, 64
	s_cmp_lg_u32 s35, 0
	s_cbranch_scc1 .LBB0_39

.LBB0_531:
	v_lshl_add_u64 v[74:75], v[28:29], 0, s[0:1]
	global_load_dword v252, v[74:75], off
	v_lshl_add_u64 v[74:75], v[26:27], 0, s[0:1]
	global_load_dword v253, v[74:75], off
	v_lshl_add_u64 v[74:75], v[20:21], 0, s[0:1]
	global_load_dword v254, v[74:75], off
	v_lshl_add_u64 v[74:75], v[16:17], 0, s[0:1]
	global_load_dword v255, v[74:75], off
	v_lshl_add_u64 v[74:75], v[30:31], 0, v[12:13]
	global_load_dwordx4 v[74:77], v[74:75], off
	v_lshl_add_u64 v[238:239], v[24:25], 0, v[12:13]
	global_load_dwordx4 v[238:241], v[238:239], off
	v_lshl_add_u64 v[242:243], v[22:23], 0, v[12:13]
	global_load_dwordx4 v[242:245], v[242:243], off
	v_lshl_add_u64 v[246:247], v[18:19], 0, v[12:13]
	global_load_dwordx4 v[246:249], v[246:247], off
	s_add_i32 s17, s16, -4
	v_lshl_add_u64 v[30:31], v[30:31], 0, s[36:37]
	v_lshl_add_u64 v[24:25], v[24:25], 0, s[36:37]
	v_lshl_add_u64 v[22:23], v[22:23], 0, s[36:37]
	v_lshl_add_u64 v[18:19], v[18:19], 0, s[36:37]
	v_xor_b32_e32 v78, s17, v32
	v_lshl_add_u32 v79, v78, 2, v4
	v_xor_b32_e32 v78, s16, v32
	v_lshl_add_u32 v78, v78, 2, v4
	s_waitcnt vmcnt(3)
	v_pk_mul_f32 v[74:75], v[74:75], v[252:253] op_sel_hi:[1,0]
	v_pk_mul_f32 v[76:77], v[76:77], v[252:253] op_sel_hi:[1,0]
	ds_write_b128 v79, v[74:77]
	s_waitcnt vmcnt(2)
	v_pk_mul_f32 v[238:239], v[238:239], v[252:253] op_sel:[0,1] op_sel_hi:[1,1]
	v_pk_mul_f32 v[240:241], v[240:241], v[252:253] op_sel:[0,1] op_sel_hi:[1,1]
	ds_write_b128 v79, v[238:241] offset:1024
	s_waitcnt vmcnt(1)
	v_pk_mul_f32 v[242:243], v[242:243], v[254:255] op_sel_hi:[1,0]
	v_pk_mul_f32 v[244:245], v[244:245], v[254:255] op_sel_hi:[1,0]
	ds_write_b128 v78, v[242:245] offset:2048
	s_waitcnt vmcnt(0)
	v_pk_mul_f32 v[246:247], v[246:247], v[254:255] op_sel:[0,1] op_sel_hi:[1,1]
	v_pk_mul_f32 v[248:249], v[248:249], v[254:255] op_sel:[0,1] op_sel_hi:[1,1]
	ds_write_b128 v78, v[246:249] offset:3072
	s_add_u32 s0, s0, 64
	s_addc_u32 s1, s1, 0
	s_add_i32 s16, s16, 8
	v_add_u32_e32 v4, 0x1000, v4
	s_cmpk_lg_i32 s0, 0x100
	s_cbranch_scc1 .LBB0_531
	s_waitcnt lgkmcnt(0)
	ds_read2st64_b32 v[16:17], v34 offset1:1
	ds_read2st64_b32 v[18:19], v34 offset0:2 offset1:3
	ds_read2st64_b32 v[20:21], v34 offset0:6 offset1:7
	s_and_b32 s0, s5, 0xfc0
	s_add_i32 s1, s0, 0xfffffa00
	s_waitcnt lgkmcnt(2)
	v_bfe_u32 v4, v16, 16, 1
	v_add3_u32 v4, v16, v4, s12
	v_bfe_u32 v16, v17, 16, 1
	v_lshrrev_b32_e32 v4, 16, v4
	v_add3_u32 v16, v17, v16, s12
	v_and_or_b32 v16, v16, s13, v4
	s_waitcnt lgkmcnt(1)
	v_bfe_u32 v4, v18, 16, 1
	v_bfe_u32 v17, v19, 16, 1
	v_add3_u32 v4, v18, v4, s12
	v_add3_u32 v17, v19, v17, s12
	ds_read2st64_b32 v[18:19], v34 offset0:4 offset1:5
	v_lshrrev_b32_e32 v4, 16, v4
	v_and_or_b32 v17, v17, s13, v4
	s_lshl_b32 s0, s5, 6
	v_bitop3_b32 v22, s0, v69, v33 bitop3:0xc8
	s_waitcnt lgkmcnt(0)
	v_bfe_u32 v4, v18, 16, 1
	v_add3_u32 v4, v18, v4, s12
	v_bfe_u32 v18, v19, 16, 1
	v_lshrrev_b32_e32 v4, 16, v4
	v_add3_u32 v18, v19, v18, s12
	v_and_or_b32 v18, v18, s13, v4
	v_bfe_u32 v4, v20, 16, 1
	v_add3_u32 v4, v20, v4, s12
	v_bfe_u32 v19, v21, 16, 1
	v_lshrrev_b32_e32 v4, 16, v4
	v_add3_u32 v19, v21, v19, s12
	s_lshr_b32 s1, s1, 6
	v_and_or_b32 v19, v19, s13, v4
	v_add_u32_e32 v4, v50, v22
	v_mad_u64_u32 v[20:21], s[16:17], s1, v70, v[4:5]
	v_lshlrev_b64 v[20:21], 7, v[20:21]
	v_lshl_add_u64 v[20:21], v[8:9], 0, v[20:21]
	global_store_dwordx4 v[20:21], v[16:19], off
	ds_read2st64_b32 v[16:17], v37 offset1:1
	ds_read2st64_b32 v[18:19], v37 offset0:2 offset1:3
	ds_read2st64_b32 v[20:21], v37 offset0:6 offset1:7
	s_waitcnt lgkmcnt(2)
	v_bfe_u32 v4, v16, 16, 1
	v_add3_u32 v4, v16, v4, s12
	v_bfe_u32 v16, v17, 16, 1
	v_lshrrev_b32_e32 v4, 16, v4
	v_add3_u32 v16, v17, v16, s12
	v_and_or_b32 v16, v16, s13, v4
	s_waitcnt lgkmcnt(1)
	v_bfe_u32 v4, v18, 16, 1
	v_bfe_u32 v17, v19, 16, 1
	v_add3_u32 v4, v18, v4, s12
	v_add3_u32 v17, v19, v17, s12
	ds_read2st64_b32 v[18:19], v37 offset0:4 offset1:5
	v_lshrrev_b32_e32 v4, 16, v4
	v_and_or_b32 v17, v17, s13, v4
	s_waitcnt lgkmcnt(0)
	v_bfe_u32 v4, v18, 16, 1
	v_add3_u32 v4, v18, v4, s12
	v_bfe_u32 v18, v19, 16, 1
	v_lshrrev_b32_e32 v4, 16, v4
	v_add3_u32 v18, v19, v18, s12
	v_and_or_b32 v18, v18, s13, v4
	v_bfe_u32 v4, v20, 16, 1
	v_add3_u32 v4, v20, v4, s12
	v_bfe_u32 v19, v21, 16, 1
	v_lshrrev_b32_e32 v4, 16, v4
	v_add3_u32 v19, v21, v19, s12
	v_and_or_b32 v19, v19, s13, v4
	v_add_u32_e32 v4, v51, v22
	v_mad_u64_u32 v[20:21], s[16:17], s1, v70, v[4:5]
	v_lshlrev_b64 v[20:21], 7, v[20:21]
	v_lshl_add_u64 v[20:21], v[8:9], 0, v[20:21]
	global_store_dwordx4 v[20:21], v[16:19], off
	ds_read2st64_b32 v[16:17], v39 offset1:1
	ds_read2st64_b32 v[18:19], v39 offset0:2 offset1:3
	ds_read2st64_b32 v[20:21], v39 offset0:6 offset1:7
	s_waitcnt lgkmcnt(2)
	v_bfe_u32 v4, v16, 16, 1
	v_add3_u32 v4, v16, v4, s12
	v_bfe_u32 v16, v17, 16, 1
	v_lshrrev_b32_e32 v4, 16, v4
	v_add3_u32 v16, v17, v16, s12
	v_and_or_b32 v16, v16, s13, v4
	s_waitcnt lgkmcnt(1)
	v_bfe_u32 v4, v18, 16, 1
	v_bfe_u32 v17, v19, 16, 1
	v_add3_u32 v4, v18, v4, s12
	v_add3_u32 v17, v19, v17, s12
	ds_read2st64_b32 v[18:19], v39 offset0:4 offset1:5
	v_lshrrev_b32_e32 v4, 16, v4
	v_and_or_b32 v17, v17, s13, v4
	s_waitcnt lgkmcnt(0)
	v_bfe_u32 v4, v18, 16, 1
	v_add3_u32 v4, v18, v4, s12
	v_bfe_u32 v18, v19, 16, 1
	v_lshrrev_b32_e32 v4, 16, v4
	v_add3_u32 v18, v19, v18, s12
	v_and_or_b32 v18, v18, s13, v4
	v_bfe_u32 v4, v20, 16, 1
	v_add3_u32 v4, v20, v4, s12
	v_bfe_u32 v19, v21, 16, 1
	v_lshrrev_b32_e32 v4, 16, v4
	v_add3_u32 v19, v21, v19, s12
	v_and_or_b32 v19, v19, s13, v4
	v_add_u32_e32 v4, v52, v22
	v_mad_u64_u32 v[20:21], s[16:17], s1, v70, v[4:5]
	v_lshlrev_b64 v[20:21], 7, v[20:21]
	v_lshl_add_u64 v[20:21], v[8:9], 0, v[20:21]
	global_store_dwordx4 v[20:21], v[16:19], off
	ds_read2st64_b32 v[16:17], v41 offset1:1
	ds_read2st64_b32 v[18:19], v41 offset0:2 offset1:3
	ds_read2st64_b32 v[20:21], v41 offset0:6 offset1:7
	s_waitcnt lgkmcnt(2)
	v_bfe_u32 v4, v16, 16, 1
	v_add3_u32 v4, v16, v4, s12
	v_bfe_u32 v16, v17, 16, 1
	v_lshrrev_b32_e32 v4, 16, v4
	v_add3_u32 v16, v17, v16, s12
	v_and_or_b32 v16, v16, s13, v4
	s_waitcnt lgkmcnt(1)
	v_bfe_u32 v4, v18, 16, 1
	v_bfe_u32 v17, v19, 16, 1
	v_add3_u32 v4, v18, v4, s12
	v_add3_u32 v17, v19, v17, s12
	ds_read2st64_b32 v[18:19], v41 offset0:4 offset1:5
	v_lshrrev_b32_e32 v4, 16, v4
	v_and_or_b32 v17, v17, s13, v4
	s_waitcnt lgkmcnt(0)
	v_bfe_u32 v4, v18, 16, 1
	v_add3_u32 v4, v18, v4, s12
	v_bfe_u32 v18, v19, 16, 1
	v_lshrrev_b32_e32 v4, 16, v4
	v_add3_u32 v18, v19, v18, s12
	v_and_or_b32 v18, v18, s13, v4
	v_bfe_u32 v4, v20, 16, 1
	v_add3_u32 v4, v20, v4, s12
	v_bfe_u32 v19, v21, 16, 1
	v_lshrrev_b32_e32 v4, 16, v4
	v_add3_u32 v19, v21, v19, s12
	v_and_or_b32 v19, v19, s13, v4
	v_add_u32_e32 v4, v53, v22
	v_mad_u64_u32 v[20:21], s[16:17], s1, v70, v[4:5]
	v_lshlrev_b64 v[20:21], 7, v[20:21]
	v_lshl_add_u64 v[20:21], v[8:9], 0, v[20:21]
	global_store_dwordx4 v[20:21], v[16:19], off
	ds_read2st64_b32 v[16:17], v43 offset1:1
	ds_read2st64_b32 v[18:19], v43 offset0:2 offset1:3
	ds_read2st64_b32 v[20:21], v43 offset0:6 offset1:7
	s_waitcnt lgkmcnt(2)
	v_bfe_u32 v4, v16, 16, 1
	v_add3_u32 v4, v16, v4, s12
	v_bfe_u32 v16, v17, 16, 1
	v_lshrrev_b32_e32 v4, 16, v4
	v_add3_u32 v16, v17, v16, s12
	v_and_or_b32 v16, v16, s13, v4
	s_waitcnt lgkmcnt(1)
	v_bfe_u32 v4, v18, 16, 1
	v_bfe_u32 v17, v19, 16, 1
	v_add3_u32 v4, v18, v4, s12
	v_add3_u32 v17, v19, v17, s12
	ds_read2st64_b32 v[18:19], v43 offset0:4 offset1:5
	v_lshrrev_b32_e32 v4, 16, v4
	v_and_or_b32 v17, v17, s13, v4
	s_waitcnt lgkmcnt(0)
	v_bfe_u32 v4, v18, 16, 1
	v_add3_u32 v4, v18, v4, s12
	v_bfe_u32 v18, v19, 16, 1
	v_lshrrev_b32_e32 v4, 16, v4
	v_add3_u32 v18, v19, v18, s12
	v_and_or_b32 v18, v18, s13, v4
	v_bfe_u32 v4, v20, 16, 1
	v_add3_u32 v4, v20, v4, s12
	v_bfe_u32 v19, v21, 16, 1
	v_lshrrev_b32_e32 v4, 16, v4
	v_add3_u32 v19, v21, v19, s12
	v_and_or_b32 v19, v19, s13, v4
	v_bitop3_b32 v4, s0, v71, v42 bitop3:0xc8
	v_add_u32_e32 v4, v50, v4
	v_mad_u64_u32 v[20:21], s[16:17], s1, v70, v[4:5]
	v_lshlrev_b64 v[20:21], 7, v[20:21]
	v_lshl_add_u64 v[20:21], v[8:9], 0, v[20:21]
	global_store_dwordx4 v[20:21], v[16:19], off
	ds_read2st64_b32 v[16:17], v45 offset1:1
	ds_read2st64_b32 v[18:19], v45 offset0:2 offset1:3
	ds_read2st64_b32 v[20:21], v45 offset0:6 offset1:7
	s_waitcnt lgkmcnt(2)
	v_bfe_u32 v4, v16, 16, 1
	v_add3_u32 v4, v16, v4, s12
	v_bfe_u32 v16, v17, 16, 1
	v_lshrrev_b32_e32 v4, 16, v4
	v_add3_u32 v16, v17, v16, s12
	v_and_or_b32 v16, v16, s13, v4
	s_waitcnt lgkmcnt(1)
	v_bfe_u32 v4, v18, 16, 1
	v_bfe_u32 v17, v19, 16, 1
	v_add3_u32 v4, v18, v4, s12
	v_add3_u32 v17, v19, v17, s12
	ds_read2st64_b32 v[18:19], v45 offset0:4 offset1:5
	v_lshrrev_b32_e32 v4, 16, v4
	v_and_or_b32 v17, v17, s13, v4
	s_waitcnt lgkmcnt(0)
	v_bfe_u32 v4, v18, 16, 1
	v_add3_u32 v4, v18, v4, s12
	v_bfe_u32 v18, v19, 16, 1
	v_lshrrev_b32_e32 v4, 16, v4
	v_add3_u32 v18, v19, v18, s12
	v_and_or_b32 v18, v18, s13, v4
	v_bfe_u32 v4, v20, 16, 1
	v_add3_u32 v4, v20, v4, s12
	v_bfe_u32 v19, v21, 16, 1
	v_lshrrev_b32_e32 v4, 16, v4
	v_add3_u32 v19, v21, v19, s12
	v_and_or_b32 v19, v19, s13, v4
	v_bitop3_b32 v4, s0, v71, v44 bitop3:0xc8
	v_add_u32_e32 v4, v51, v4
	v_mad_u64_u32 v[20:21], s[16:17], s1, v70, v[4:5]
	v_lshlrev_b64 v[20:21], 7, v[20:21]
	v_lshl_add_u64 v[20:21], v[8:9], 0, v[20:21]
	global_store_dwordx4 v[20:21], v[16:19], off
	ds_read2st64_b32 v[16:17], v47 offset1:1
	ds_read2st64_b32 v[18:19], v47 offset0:2 offset1:3
	ds_read2st64_b32 v[20:21], v47 offset0:6 offset1:7
	s_waitcnt lgkmcnt(2)
	v_bfe_u32 v4, v16, 16, 1
	v_add3_u32 v4, v16, v4, s12
	v_bfe_u32 v16, v17, 16, 1
	v_lshrrev_b32_e32 v4, 16, v4
	v_add3_u32 v16, v17, v16, s12
	v_and_or_b32 v16, v16, s13, v4
	s_waitcnt lgkmcnt(1)
	v_bfe_u32 v4, v18, 16, 1
	v_bfe_u32 v17, v19, 16, 1
	v_add3_u32 v4, v18, v4, s12
	v_add3_u32 v17, v19, v17, s12
	ds_read2st64_b32 v[18:19], v47 offset0:4 offset1:5
	v_lshrrev_b32_e32 v4, 16, v4
	v_and_or_b32 v17, v17, s13, v4
	s_waitcnt lgkmcnt(0)
	v_bfe_u32 v4, v18, 16, 1
	v_add3_u32 v4, v18, v4, s12
	v_bfe_u32 v18, v19, 16, 1
	v_lshrrev_b32_e32 v4, 16, v4
	v_add3_u32 v18, v19, v18, s12
	v_and_or_b32 v18, v18, s13, v4
	v_bfe_u32 v4, v20, 16, 1
	v_add3_u32 v4, v20, v4, s12
	v_bfe_u32 v19, v21, 16, 1
	v_lshrrev_b32_e32 v4, 16, v4
	v_add3_u32 v19, v21, v19, s12
	v_and_or_b32 v19, v19, s13, v4
	v_bitop3_b32 v4, s0, v71, v46 bitop3:0xc8
	v_add_u32_e32 v4, v52, v4
	v_mad_u64_u32 v[20:21], s[16:17], s1, v70, v[4:5]
	v_lshlrev_b64 v[20:21], 7, v[20:21]
	v_lshl_add_u64 v[20:21], v[8:9], 0, v[20:21]
	global_store_dwordx4 v[20:21], v[16:19], off
	ds_read2st64_b32 v[16:17], v49 offset1:1
	ds_read2st64_b32 v[18:19], v49 offset0:2 offset1:3
	ds_read2st64_b32 v[20:21], v49 offset0:6 offset1:7
	s_waitcnt lgkmcnt(2)
	v_bfe_u32 v4, v16, 16, 1
	v_add3_u32 v4, v16, v4, s12
	v_bfe_u32 v16, v17, 16, 1
	v_lshrrev_b32_e32 v4, 16, v4
	v_add3_u32 v16, v17, v16, s12
	v_and_or_b32 v16, v16, s13, v4
	s_waitcnt lgkmcnt(1)
	v_bfe_u32 v4, v18, 16, 1
	v_bfe_u32 v17, v19, 16, 1
	v_add3_u32 v4, v18, v4, s12
	v_add3_u32 v17, v19, v17, s12
	ds_read2st64_b32 v[18:19], v49 offset0:4 offset1:5
	v_lshrrev_b32_e32 v4, 16, v4
	v_and_or_b32 v17, v17, s13, v4
	s_waitcnt lgkmcnt(0)
	v_bfe_u32 v4, v18, 16, 1
	v_add3_u32 v4, v18, v4, s12
	v_bfe_u32 v18, v19, 16, 1
	v_lshrrev_b32_e32 v4, 16, v4
	v_add3_u32 v18, v19, v18, s12
	v_and_or_b32 v18, v18, s13, v4
	v_bfe_u32 v4, v20, 16, 1
	v_add3_u32 v4, v20, v4, s12
	v_bfe_u32 v19, v21, 16, 1
	v_lshrrev_b32_e32 v4, 16, v4
	v_add3_u32 v19, v21, v19, s12
	v_and_or_b32 v19, v19, s13, v4
	v_bitop3_b32 v4, s0, v71, v48 bitop3:0xc8
	v_add_u32_e32 v4, v53, v4
	v_mad_u64_u32 v[20:21], s[0:1], s1, v70, v[4:5]
	v_lshlrev_b64 v[20:21], 7, v[20:21]
	v_lshl_add_u64 v[20:21], v[8:9], 0, v[20:21]
	global_store_dwordx4 v[20:21], v[16:19], off
	s_waitcnt lgkmcnt(0)

.LBB0_537:
	v_mov_b32_e32 v252, 1.0
	v_mov_b32_e32 v253, 1.0
	v_mov_b32_e32 v254, 1.0
	v_mov_b32_e32 v255, 1.0
	s_andn2_b64 vcc, exec, s[22:23]
	s_cbranch_vccnz .Lp3b_nogain
	v_add_u32_e32 v22, -12, v18
	v_ashrrev_i32_e32 v23, 31, v22
	v_lshl_add_u64 v[24:25], v[22:23], 2, s[48:49]
	global_load_dword v252, v[24:25], off
	global_load_dword v253, v[20:21], off
	v_add_u32_e32 v22, -4, v18
	v_ashrrev_i32_e32 v23, 31, v22
	v_lshl_add_u64 v[24:25], v[22:23], 2, s[48:49]
	global_load_dword v254, v[24:25], off
	v_ashrrev_i32_e32 v19, 31, v18
	v_lshl_add_u64 v[24:25], v[18:19], 2, s[48:49]
	global_load_dword v255, v[24:25], off
.Lp3b_nogain:
	v_add_u32_e32 v22, -12, v18
	v_mad_i64_i32 v[26:27], s[38:39], v22, s14, v[16:17]
	global_load_dwordx4 v[26:29], v[26:27], off
	v_add_u32_e32 v22, -8, v18
	v_mad_i64_i32 v[238:239], s[38:39], v22, s14, v[16:17]
	global_load_dwordx4 v[238:241], v[238:239], off
	v_add_u32_e32 v22, -4, v18
	v_mad_i64_i32 v[242:243], s[38:39], v22, s14, v[16:17]
	global_load_dwordx4 v[242:245], v[242:243], off
	v_mad_i64_i32 v[246:247], s[38:39], v18, s14, v[16:17]
	global_load_dwordx4 v[246:249], v[246:247], off
	s_add_i32 s24, s17, -4
	v_xor_b32_e32 v19, s24, v32
	v_lshl_add_u32 v19, v19, 2, v57
	v_add_u32_e32 v19, s1, v19
	v_xor_b32_e32 v22, s17, v32
	v_lshl_add_u32 v22, v22, 2, v57
	v_add_u32_e32 v22, s1, v22
	s_waitcnt vmcnt(3)
	v_pk_mul_f32 v[26:27], v[26:27], v[252:253] op_sel_hi:[1,0]
	v_pk_mul_f32 v[28:29], v[28:29], v[252:253] op_sel_hi:[1,0]
	ds_write_b128 v19, v[26:29] offset:16384
	s_waitcnt vmcnt(2)
	v_pk_mul_f32 v[238:239], v[238:239], v[252:253] op_sel:[0,1] op_sel_hi:[1,1]
	v_pk_mul_f32 v[240:241], v[240:241], v[252:253] op_sel:[0,1] op_sel_hi:[1,1]
	ds_write_b128 v19, v[238:241] offset:17408
	s_waitcnt vmcnt(1)
	v_pk_mul_f32 v[242:243], v[242:243], v[254:255] op_sel_hi:[1,0]
	v_pk_mul_f32 v[244:245], v[244:245], v[254:255] op_sel_hi:[1,0]
	ds_write_b128 v22, v[242:245] offset:18432
	s_waitcnt vmcnt(0)
	v_pk_mul_f32 v[246:247], v[246:247], v[254:255] op_sel:[0,1] op_sel_hi:[1,1]
	v_pk_mul_f32 v[248:249], v[248:249], v[254:255] op_sel:[0,1] op_sel_hi:[1,1]
	ds_write_b128 v22, v[246:249] offset:19456
	s_addk_i32 s1, 0x1000
	s_add_i32 s17, s17, 8
	v_add_u32_e32 v18, 16, v18
	v_lshl_add_u64 v[20:21], v[20:21], 0, 64
	s_cmp_lg_u32 s1, 0
	s_cbranch_scc1 .LBB0_537
	s_branch .LBB0_522
